# attention A loop: first-block V transposed reads (and in the odd step the P->bf16 converts) issued before the LDS-DMA issue block so their LDS latency hides under it
# speedup vs baseline: 1.0039x; 1.0039x over previous
; template <int OFF> __device__ __forceinline__ s16x4 tr_read(int vb) { s16x4 r; asm volatile("ds_read_b64_tr_b16 %0, %1 offset:%2" : "=&v"(r) : "v"(vb), "i"(OFF) : "memory"); return r; }
; __device__ __forceinline__ void finishSM(f32x16& p0, f32x16& p1, float alpha, float& l_reg, bf16x8& pa0, bf16x8& pa1, bf16x8& pa2, bf16x8& pa3) {
; #pragma unroll
;   for (int r = 0; r < 16; ++r) p1[r] = __builtin_amdgcn_exp2f(p1[r]);
;   float ps = 0;
; #pragma unroll
;   for (int r = 0; r < 16; ++r) ps += p0[r];
; #pragma unroll
;   for (int r = 0; r < 16; ++r) ps += p1[r];
;   { auto rr = __builtin_amdgcn_permlane32_swap(__float_as_uint(ps), __float_as_uint(ps), false, false);
;     ps = __uint_as_float(rr[0]) + __uint_as_float(rr[1]); }
;   l_reg = l_reg * alpha + ps;
;     ...
;   ATT_PKN(p0, 0, pa0); ATT_PKN(p0, 8, pa1); ATT_PKN(p1, 0, pa2); ATT_PKN(p1, 8, pa3);
;     ...
; }
; __device__ __forceinline__ void qkt(f32x16& p0, f32x16& p1, const bf16* Ks, const bf16x8* qr, int r32, int hi, int mp, const f32x16& negm) {
; #pragma unroll
;   for (int d0 = 0; d0 < 4; ++d0) { int cb = ((mp * 4 + d0) * 16 + hi * 8) * 2;
;     bf16x8 b0 = *reinterpret_cast<const bf16x8*>((const char*)Ks + KSWZ(r32, cb));
;     bf16x8 b1 = *reinterpret_cast<const bf16x8*>((const char*)Ks + KSWZ(32 + r32, cb));
;     if (d0 == 0) { p0 = __builtin_amdgcn_mfma_f32_32x32x16_bf16(b0, qr[0], negm, 0, 0, 0); p1 = __builtin_amdgcn_mfma_f32_32x32x16_bf16(b1, qr[0], negm, 0, 0, 0); }
;     else { p0 = __builtin_amdgcn_mfma_f32_32x32x16_bf16(b0, qr[d0], p0, 0, 0, 0); p1 = __builtin_amdgcn_mfma_f32_32x32x16_bf16(b1, qr[d0], p1, 0, 0, 0); } }
; }
; __device__ __forceinline__ int v_st(int k, int c) { const int kk = k; return ((kk >> 3) * 4 + (c >> 5)) * 512 + ((kk & 7) * 32 + (c & 31)) * 2; }
; template <int D0> __device__ __forceinline__ void pv_one(f32x16& od, int vb, bf16x8 pa0, bf16x8 pa1, bf16x8 pa2, bf16x8 pa3) {
;   const s16x4 l0 = tr_read<v_rd_off(D0, 0, 0)>(vb), h0 = tr_read<v_rd_off(D0, 0, 1)>(vb), l1 = tr_read<v_rd_off(D0, 1, 0)>(vb), h1 = tr_read<v_rd_off(D0, 1, 1)>(vb);
;   const s16x4 l2 = tr_read<v_rd_off(D0, 2, 0)>(vb), h2 = tr_read<v_rd_off(D0, 2, 1)>(vb), l3 = tr_read<v_rd_off(D0, 3, 0)>(vb), h3 = tr_read<v_rd_off(D0, 3, 1)>(vb);
.LBB0_197:
	s_add_i32 s10, s39, 0
	v_add_u32_e32 v112, s10, v202
	ds_read_b128 v[236:239], v112 offset:24576
	ds_read_b128 v[112:115], v112 offset:16384
	v_add_u32_e32 v208, s10, v201
	v_exp_f32_e32 v210, v96
	v_add_f32_e32 v96, 0, v172
	v_add_f32_e32 v96, v174, v96
	s_waitcnt lgkmcnt(0)
	v_mfma_f32_32x32x16_bf16 v[128:143], v[112:115], v[158:161], v[80:95]
	v_mov_b64_e32 v[126:127], v[94:95]
	v_mov_b64_e32 v[124:125], v[92:93]
	v_mov_b64_e32 v[122:123], v[90:91]
	v_mov_b64_e32 v[120:121], v[88:89]
	v_mov_b64_e32 v[118:119], v[86:87]
	v_mov_b64_e32 v[116:117], v[84:85]
	v_mov_b64_e32 v[114:115], v[82:83]
	v_mov_b64_e32 v[112:113], v[80:81]
	v_add_f32_e32 v96, v175, v96
	v_add_f32_e32 v96, v211, v96
	v_mfma_f32_32x32x16_bf16 v[112:127], v[236:239], v[158:161], v[112:127]
	ds_read_b128 v[236:239], v208 offset:24576
	ds_read_b128 v[240:243], v208 offset:16384
	v_add_u32_e32 v208, s10, v199
	v_add_f32_e32 v96, v212, v96
	v_add_f32_e32 v96, v215, v96
	v_add_f32_e32 v96, v216, v96
	v_add_f32_e32 v96, v233, v96
	v_add_f32_e32 v96, v173, v96
	s_waitcnt lgkmcnt(0)
	v_mfma_f32_32x32x16_bf16 v[112:127], v[236:239], v[154:157], v[112:127]
	v_add_f32_e32 v96, v176, v96
	v_add_f32_e32 v96, v177, v96
	v_add_f32_e32 v96, v213, v96
	v_add_f32_e32 v96, v214, v96
	v_exp_f32_e32 v235, v97
	v_add_f32_e32 v96, v217, v96
	v_add_f32_e32 v96, v232, v96
	s_waitcnt lgkmcnt(0)
	v_mfma_f32_32x32x16_bf16 v[128:143], v[240:243], v[154:157], v[128:143]
	ds_read_b128 v[236:239], v208 offset:24576
	ds_read_b128 v[240:243], v208 offset:16384
	v_add_u32_e32 v208, s10, v183
	v_add_f32_e32 v96, v234, v96
	v_add_f32_e32 v96, v210, v96
	v_add_f32_e32 v96, v235, v96
	v_exp_f32_e32 v244, v106
	v_exp_f32_e32 v245, v107
	s_waitcnt lgkmcnt(0)
	v_mfma_f32_32x32x16_bf16 v[112:127], v[236:239], v[150:153], v[112:127]
	v_exp_f32_e32 v246, v108
	v_exp_f32_e32 v247, v109
	v_exp_f32_e32 v248, v110
	v_exp_f32_e32 v111, v111
	v_cvt_pk_bf16_f32 v97, v175, v211
	v_cvt_pk_bf16_f32 v109, v244, v245
	v_cvt_pk_bf16_f32 v110, v246, v247
	s_waitcnt lgkmcnt(0)
	v_mfma_f32_32x32x16_bf16 v[128:143], v[240:243], v[150:153], v[128:143]
	ds_read_b128 v[236:239], v208 offset:24576
	ds_read_b128 v[240:243], v208 offset:16384
	s_waitcnt lgkmcnt(0)
	v_mfma_f32_32x32x16_bf16 v[112:127], v[236:239], v[146:149], v[112:127]
	v_exp_f32_e32 v236, v98
	v_exp_f32_e32 v237, v99
	v_exp_f32_e32 v238, v100
	v_exp_f32_e32 v239, v101
	v_add_f32_e32 v96, v236, v96
	v_add_f32_e32 v96, v237, v96
	v_add_f32_e32 v96, v238, v96
	s_waitcnt lgkmcnt(0)
	v_mfma_f32_32x32x16_bf16 v[128:143], v[240:243], v[146:149], v[128:143]
	v_exp_f32_e32 v240, v102
	v_exp_f32_e32 v241, v103
	v_exp_f32_e32 v242, v104
	v_exp_f32_e32 v243, v105
	v_add_f32_e32 v96, v239, v96
	v_add_f32_e32 v96, v240, v96
	v_add_f32_e32 v96, v241, v96
	v_add_f32_e32 v96, v242, v96
	v_add_f32_e32 v96, v243, v96
	v_add_f32_e32 v96, v244, v96
	v_add_f32_e32 v96, v245, v96
	v_add_f32_e32 v96, v246, v96
	v_add_f32_e32 v96, v247, v96
	v_add_f32_e32 v96, v248, v96
	v_add_f32_e32 v208, v111, v96
	v_mov_b32_e32 v209, v208
	s_nop 1
	v_permlane32_swap_b32_e32 v208, v209
	v_cvt_pk_bf16_f32 v96, v172, v174
	v_cvt_pk_bf16_f32 v98, v212, v215
	v_cvt_pk_bf16_f32 v99, v216, v233
	v_cvt_pk_bf16_f32 v100, v173, v176
	v_cvt_pk_bf16_f32 v101, v177, v213
	v_cvt_pk_bf16_f32 v102, v214, v217
	v_cvt_pk_bf16_f32 v103, v232, v234
	v_cvt_pk_bf16_f32 v104, v210, v235
	v_cvt_pk_bf16_f32 v105, v236, v237
	v_cvt_pk_bf16_f32 v106, v238, v239
	v_cvt_pk_bf16_f32 v107, v240, v241
	v_cvt_pk_bf16_f32 v108, v242, v243
	v_cvt_pk_bf16_f32 v111, v248, v111
	v_add_u32_e32 v240, s48, v205
	ds_read_b64_tr_b16 v[210:211], v240 offset:0
	ds_read_b64_tr_b16 v[212:213], v240 offset:0x800
	ds_read_b64_tr_b16 v[214:215], v240 offset:0x1000
	ds_read_b64_tr_b16 v[216:217], v240 offset:0x1800
	ds_read_b64_tr_b16 v[232:233], v240 offset:0x2000
	ds_read_b64_tr_b16 v[234:235], v240 offset:0x2800
	ds_read_b64_tr_b16 v[236:237], v240 offset:0x3000
	ds_read_b64_tr_b16 v[238:239], v240 offset:0x3800
	v_lshl_add_u64 v[174:175], s[50:51], 0, v[168:169]
	s_add_i32 s12, s21, s56
	v_lshl_add_u64 v[172:173], v[174:175], 0, s[36:37]
	s_add_i32 m0, s12, 0x4000
	s_mov_b64 s[10:11], 0x4030000
	global_load_lds_dwordx4 v[172:173], off
	v_lshl_add_u64 v[172:173], s[50:51], 0, v[188:189]
	v_lshl_add_u64 v[176:177], v[172:173], 0, s[10:11]
	s_mov_b32 m0, s12
	s_mov_b64 s[10:11], 0x4030080
	global_load_lds_dwordx4 v[176:177], off
	v_lshl_add_u64 v[176:177], s[50:51], 0, v[170:171]
	v_lshl_add_u64 v[66:67], v[176:177], 0, s[36:37]
	s_add_i32 m0, s12, 0x4400
	s_nop 0
	global_load_lds_dwordx4 v[66:67], off
	v_lshl_add_u64 v[66:67], v[172:173], 0, s[10:11]
	s_add_i32 m0, s12, 0x400
	s_nop 0
	global_load_lds_dwordx4 v[66:67], off
	s_waitcnt lgkmcnt(0)
; #define SBAR() __builtin_amdgcn_sched_barrier(0)
; template <int OFF> __device__ __forceinline__ s16x4 tr_read(int vb) { s16x4 r; asm volatile("ds_read_b64_tr_b16 %0, %1 offset:%2" : "=&v"(r) : "v"(vb), "i"(OFF) : "memory"); return r; }
; template <bool FIRST> __device__ __forceinline__ void partialSM(f32x16& p0, f32x16& p1, float& m_reg, f32x16& negm, float& alpha) {
;   float pmax = p0[0];
; #pragma unroll
;   for (int r = 1; r < 16; ++r) pmax = fmaxf(pmax, p0[r]);
; #pragma unroll
;   for (int r = 0; r < 16; ++r) pmax = fmaxf(pmax, p1[r]);
;   { auto rr = __builtin_amdgcn_permlane32_swap(__float_as_uint(pmax), __float_as_uint(pmax), false, false);
;     pmax = fmaxf(__uint_as_float(rr[0]), __uint_as_float(rr[1])); }
;   alpha = 1.f;
;   if (FIRST || __builtin_expect(__any(pmax > THR), 0)) { const float dl = FIRST ? pmax : fmaxf(pmax, 0.f); m_reg += dl; if (!FIRST) alpha = __builtin_amdgcn_exp2f(-dl);
; template <int D0> __device__ __forceinline__ void pv_one(f32x16& od, int vb, bf16x8 pa0, bf16x8 pa1, bf16x8 pa2, bf16x8 pa3) {
;   const s16x4 l0 = tr_read<v_rd_off(D0, 0, 0)>(vb), h0 = tr_read<v_rd_off(D0, 0, 1)>(vb), l1 = tr_read<v_rd_off(D0, 1, 0)>(vb), h1 = tr_read<v_rd_off(D0, 1, 1)>(vb);
;   const s16x4 l2 = tr_read<v_rd_off(D0, 2, 0)>(vb), h2 = tr_read<v_rd_off(D0, 2, 1)>(vb), l3 = tr_read<v_rd_off(D0, 3, 0)>(vb), h3 = tr_read<v_rd_off(D0, 3, 1)>(vb);
;   asm volatile("s_waitcnt lgkmcnt(0)" ::: "memory"); SBAR();
;   od = __builtin_amdgcn_mfma_f32_32x32x16_bf16(pa0, ATT_PK(l0, h0), od, 0, 0, 0);
;   od = __builtin_amdgcn_mfma_f32_32x32x16_bf16(pa1, ATT_PK(l1, h1), od, 0, 0, 0);
;   od = __builtin_amdgcn_mfma_f32_32x32x16_bf16(pa2, ATT_PK(l2, h2), od, 0, 0, 0);
;   od = __builtin_amdgcn_mfma_f32_32x32x16_bf16(pa3, ATT_PK(l3, h3), od, 0, 0, 0);
; }
; __device__ __forceinline__ void pv_d0(f32x16* o, int vb, bf16x8 pa0, bf16x8 pa1, bf16x8 pa2, bf16x8 pa3) {
;   pv_one<0>(o[0], vb, pa0, pa1, pa2, pa3); pv_one<1>(o[1], vb, pa0, pa1, pa2, pa3); pv_one<2>(o[2], vb, pa0, pa1, pa2, pa3); pv_one<3>(o[3], vb, pa0, pa1, pa2, pa3);
; }
	s_nop 0
	v_mfma_f32_32x32x16_bf16 v[0:15], v[96:99], v[210:213], v[0:15]
	ds_read_b64_tr_b16 v[210:211], v240 offset:0x200
	ds_read_b64_tr_b16 v[212:213], v240 offset:0xa00
	v_mfma_f32_32x32x16_bf16 v[0:15], v[100:103], v[214:217], v[0:15]
	ds_read_b64_tr_b16 v[214:215], v240 offset:0x1200
	ds_read_b64_tr_b16 v[216:217], v240 offset:0x1a00
	v_mfma_f32_32x32x16_bf16 v[0:15], v[104:107], v[232:235], v[0:15]
	ds_read_b64_tr_b16 v[232:233], v240 offset:0x2200
	ds_read_b64_tr_b16 v[234:235], v240 offset:0x2a00
	v_mfma_f32_32x32x16_bf16 v[0:15], v[108:111], v[236:239], v[0:15]
	ds_read_b64_tr_b16 v[236:237], v240 offset:0x3200
	ds_read_b64_tr_b16 v[238:239], v240 offset:0x3a00
	s_waitcnt lgkmcnt(0)
	v_mfma_f32_32x32x16_bf16 v[48:63], v[96:99], v[210:213], v[48:63]
	ds_read_b64_tr_b16 v[210:211], v240 offset:0x400
	ds_read_b64_tr_b16 v[212:213], v240 offset:0xc00
	v_mfma_f32_32x32x16_bf16 v[48:63], v[100:103], v[214:217], v[48:63]
	ds_read_b64_tr_b16 v[214:215], v240 offset:0x1400
	ds_read_b64_tr_b16 v[216:217], v240 offset:0x1c00
	v_mfma_f32_32x32x16_bf16 v[48:63], v[104:107], v[232:235], v[48:63]
	ds_read_b64_tr_b16 v[232:233], v240 offset:0x2400
	ds_read_b64_tr_b16 v[234:235], v240 offset:0x2c00
	v_mfma_f32_32x32x16_bf16 v[48:63], v[108:111], v[236:239], v[48:63]
	ds_read_b64_tr_b16 v[236:237], v240 offset:0x3400
	ds_read_b64_tr_b16 v[238:239], v240 offset:0x3c00
	s_waitcnt lgkmcnt(0)
	v_mfma_f32_32x32x16_bf16 v[32:47], v[96:99], v[210:213], v[32:47]
	ds_read_b64_tr_b16 v[210:211], v240 offset:0x600
	ds_read_b64_tr_b16 v[212:213], v240 offset:0xe00
	v_mfma_f32_32x32x16_bf16 v[32:47], v[100:103], v[214:217], v[32:47]
	ds_read_b64_tr_b16 v[214:215], v240 offset:0x1600
	ds_read_b64_tr_b16 v[216:217], v240 offset:0x1e00
	v_mfma_f32_32x32x16_bf16 v[32:47], v[104:107], v[232:235], v[32:47]
	ds_read_b64_tr_b16 v[232:233], v240 offset:0x2600
	ds_read_b64_tr_b16 v[234:235], v240 offset:0x2e00
	v_mfma_f32_32x32x16_bf16 v[32:47], v[108:111], v[236:239], v[32:47]
	ds_read_b64_tr_b16 v[236:237], v240 offset:0x3600
	ds_read_b64_tr_b16 v[238:239], v240 offset:0x3e00
	s_waitcnt lgkmcnt(0)
	v_mfma_f32_32x32x16_bf16 v[16:31], v[96:99], v[210:213], v[16:31]
	v_max_f32_e32 v96, v129, v129
	v_max_f32_e32 v97, v128, v128
	v_max_f32_e32 v96, v97, v96
	v_max3_f32 v96, v96, v130, v131
	v_max3_f32 v96, v96, v132, v133
	v_max3_f32 v96, v96, v134, v135
	v_max3_f32 v96, v96, v136, v137
	v_mfma_f32_32x32x16_bf16 v[16:31], v[100:103], v[214:217], v[16:31]
	v_max3_f32 v96, v96, v138, v139
	v_max3_f32 v96, v96, v140, v141
	v_max3_f32 v96, v96, v142, v143
	v_max3_f32 v96, v96, v112, v113
	v_max3_f32 v96, v96, v114, v115
	v_max3_f32 v96, v96, v116, v117
	v_max3_f32 v96, v96, v118, v119
	v_mfma_f32_32x32x16_bf16 v[16:31], v[104:107], v[232:235], v[16:31]
	v_max3_f32 v96, v96, v120, v121
	v_max3_f32 v96, v96, v122, v123
	v_max3_f32 v96, v96, v124, v125
	v_max3_f32 v96, v96, v126, v127
	v_mov_b32_e32 v97, v96
	s_nop 1
	v_permlane32_swap_b32_e32 v96, v97
	v_mfma_f32_32x32x16_bf16 v[16:31], v[108:111], v[236:239], v[16:31]
	v_max_f32_e32 v97, v97, v97
	v_max_f32_e32 v96, v96, v96
	v_max_f32_e32 v96, v96, v97
	v_cmp_lt_f32_e32 vcc, s19, v96
	s_cbranch_vccnz .LBB0_215
	v_mov_b64_e32 v[64:65], v[80:81]
	v_mov_b64_e32 v[66:67], v[82:83]
	v_mov_b64_e32 v[68:69], v[84:85]
	v_mov_b64_e32 v[70:71], v[86:87]
	v_mov_b64_e32 v[72:73], v[88:89]
	v_mov_b64_e32 v[74:75], v[90:91]
	v_mov_b64_e32 v[76:77], v[92:93]
	v_mov_b64_e32 v[78:79], v[94:95]
	v_mov_b32_e32 v210, 1.0
	v_cmp_gt_f32_e32 vcc, 1.0, v210
	s_cbranch_vccz .LBB0_202

; template <bool FIRST> __device__ __forceinline__ void partialSM(f32x16& p0, f32x16& p1, float& m_reg, f32x16& negm, float& alpha) {
;     ...
;   for (int r = 0; r < 16; ++r) p0[r] = __builtin_amdgcn_exp2f(p0[r]);
; }
; __device__ __forceinline__ void finishSM(f32x16& p0, f32x16& p1, float alpha, float& l_reg, bf16x8& pa0, bf16x8& pa1, bf16x8& pa2, bf16x8& pa3) {
; #pragma unroll
;   for (int r = 0; r < 16; ++r) p1[r] = __builtin_amdgcn_exp2f(p1[r]);
;   float ps = 0;
; #pragma unroll
;   for (int r = 0; r < 16; ++r) ps += p0[r];
; #pragma unroll
;   for (int r = 0; r < 16; ++r) ps += p1[r];
;   { auto rr = __builtin_amdgcn_permlane32_swap(__float_as_uint(ps), __float_as_uint(ps), false, false);
;     ps = __uint_as_float(rr[0]) + __uint_as_float(rr[1]); }
;   l_reg = l_reg * alpha + ps;
;     ...
;   ATT_PKN(p0, 0, pa0); ATT_PKN(p0, 8, pa1); ATT_PKN(p1, 0, pa2); ATT_PKN(p1, 8, pa3);
;     ...
; }
; __device__ __forceinline__ void qkt(f32x16& p0, f32x16& p1, const bf16* Ks, const bf16x8* qr, int r32, int hi, int mp, const f32x16& negm) {
; #pragma unroll
;   for (int d0 = 0; d0 < 4; ++d0) { int cb = ((mp * 4 + d0) * 16 + hi * 8) * 2;
;     bf16x8 b0 = *reinterpret_cast<const bf16x8*>((const char*)Ks + KSWZ(r32, cb));
;     bf16x8 b1 = *reinterpret_cast<const bf16x8*>((const char*)Ks + KSWZ(32 + r32, cb));
;     if (d0 == 0) { p0 = __builtin_amdgcn_mfma_f32_32x32x16_bf16(b0, qr[0], negm, 0, 0, 0); p1 = __builtin_amdgcn_mfma_f32_32x32x16_bf16(b1, qr[0], negm, 0, 0, 0); }
;     else { p0 = __builtin_amdgcn_mfma_f32_32x32x16_bf16(b0, qr[d0], p0, 0, 0, 0); p1 = __builtin_amdgcn_mfma_f32_32x32x16_bf16(b1, qr[d0], p1, 0, 0, 0); } }
; }
; __device__ __forceinline__ int v_st(int k, int c) { const int kk = k; return ((kk >> 3) * 4 + (c >> 5)) * 512 + ((kk & 7) * 32 + (c & 31)) * 2; }
; template <int D0> __device__ __forceinline__ void pv_one(f32x16& od, int vb, bf16x8 pa0, bf16x8 pa1, bf16x8 pa2, bf16x8 pa3) {
;   const s16x4 l0 = tr_read<v_rd_off(D0, 0, 0)>(vb), h0 = tr_read<v_rd_off(D0, 0, 1)>(vb), l1 = tr_read<v_rd_off(D0, 1, 0)>(vb), h1 = tr_read<v_rd_off(D0, 1, 1)>(vb);
;   const s16x4 l2 = tr_read<v_rd_off(D0, 2, 0)>(vb), h2 = tr_read<v_rd_off(D0, 2, 1)>(vb), l3 = tr_read<v_rd_off(D0, 3, 0)>(vb), h3 = tr_read<v_rd_off(D0, 3, 1)>(vb);
.LBB0_202:
	v_exp_f32_e32 v211, v128
	v_exp_f32_e32 v213, v129
	v_exp_f32_e32 v214, v130
	v_exp_f32_e32 v217, v131
	v_exp_f32_e32 v232, v132
	v_exp_f32_e32 v235, v133
	v_exp_f32_e32 v236, v134
	v_exp_f32_e32 v239, v135
	v_exp_f32_e32 v212, v136
	v_exp_f32_e32 v215, v137
	v_exp_f32_e32 v216, v138
	v_exp_f32_e32 v233, v139
	v_exp_f32_e32 v234, v140
	v_exp_f32_e32 v237, v141
	v_exp_f32_e32 v238, v142
	v_exp_f32_e32 v240, v143
	s_waitcnt vmcnt(4) lgkmcnt(0)
	s_barrier
	s_add_i32 s10, s39, 0x8000
	s_and_b32 s48, s10, 0x1ffff
	s_add_i32 s10, s48, 0
	v_add_u32_e32 v96, s10, v202
	ds_read_b128 v[242:245], v96 offset:24576
	ds_read_b128 v[96:99], v96 offset:16384
	v_add_u32_e32 v241, s10, v201
	v_exp_f32_e32 v112, v112
	v_exp_f32_e32 v115, v115
	v_exp_f32_e32 v116, v116
	s_waitcnt lgkmcnt(0)
	v_mfma_f32_32x32x16_bf16 v[128:143], v[96:99], v[158:161], v[64:79]
	v_exp_f32_e32 v117, v117
	v_exp_f32_e32 v118, v118
	v_mfma_f32_32x32x16_bf16 v[96:111], v[242:245], v[158:161], v[64:79]
	ds_read_b128 v[242:245], v241 offset:24576
	ds_read_b128 v[246:249], v241 offset:16384
	v_add_u32_e32 v241, s10, v199
	s_waitcnt lgkmcnt(0)
	v_mfma_f32_32x32x16_bf16 v[128:143], v[246:249], v[154:157], v[128:143]
	v_mfma_f32_32x32x16_bf16 v[96:111], v[242:245], v[154:157], v[96:111]
	ds_read_b128 v[242:245], v241 offset:24576
	ds_read_b128 v[246:249], v241 offset:16384
	v_add_u32_e32 v241, s10, v183
	s_waitcnt lgkmcnt(0)
	v_mfma_f32_32x32x16_bf16 v[128:143], v[246:249], v[150:153], v[128:143]
	v_mfma_f32_32x32x16_bf16 v[96:111], v[242:245], v[150:153], v[96:111]
	ds_read_b128 v[242:245], v241 offset:24576
	ds_read_b128 v[246:249], v241 offset:16384
	v_exp_f32_e32 v241, v113
	v_add_f32_e32 v113, 0, v211
	v_add_f32_e32 v113, v213, v113
	v_add_f32_e32 v113, v214, v113
	v_add_f32_e32 v113, v217, v113
	v_add_f32_e32 v113, v232, v113
	v_add_f32_e32 v113, v235, v113
	v_add_f32_e32 v113, v236, v113
	v_add_f32_e32 v113, v239, v113
	v_add_f32_e32 v113, v212, v113
	v_add_f32_e32 v113, v215, v113
	v_add_f32_e32 v113, v216, v113
	v_add_f32_e32 v113, v233, v113
	v_add_f32_e32 v113, v234, v113
	v_add_f32_e32 v113, v237, v113
	s_waitcnt lgkmcnt(0)
	v_mfma_f32_32x32x16_bf16 v[96:111], v[242:245], v[146:149], v[96:111]
	v_exp_f32_e32 v242, v114
	v_add_f32_e32 v113, v238, v113
	v_add_f32_e32 v113, v240, v113
	v_add_f32_e32 v113, v112, v113
	v_add_f32_e32 v113, v241, v113
	v_add_f32_e32 v113, v242, v113
	v_exp_f32_e32 v243, v119
	v_add_f32_e32 v113, v115, v113
	v_exp_f32_e32 v119, v120
	v_add_f32_e32 v113, v116, v113
	v_exp_f32_e32 v120, v121
	v_add_f32_e32 v113, v117, v113
	v_exp_f32_e32 v121, v122
	v_add_f32_e32 v113, v118, v113
	v_exp_f32_e32 v122, v123
	v_add_f32_e32 v113, v243, v113
	v_exp_f32_e32 v123, v124
	v_add_f32_e32 v113, v119, v113
	v_exp_f32_e32 v124, v125
	v_add_f32_e32 v113, v120, v113
	v_mfma_f32_32x32x16_bf16 v[128:143], v[246:249], v[146:149], v[128:143]
	v_exp_f32_e32 v125, v126
	v_add_f32_e32 v113, v121, v113
	v_exp_f32_e32 v126, v127
	v_add_f32_e32 v113, v122, v113
	v_add_f32_e32 v113, v123, v113
	v_add_f32_e32 v113, v124, v113
	v_add_f32_e32 v113, v125, v113
	v_add_f32_e32 v113, v126, v113
	v_mov_b32_e32 v114, v113
	s_nop 1
	v_permlane32_swap_b32_e32 v113, v114
	v_cvt_pk_bf16_f32 v250, v211, v213
	v_cvt_pk_bf16_f32 v251, v214, v217
	v_cvt_pk_bf16_f32 v252, v232, v235
	v_cvt_pk_bf16_f32 v253, v236, v239
	v_cvt_pk_bf16_f32 v212, v212, v215
	v_cvt_pk_bf16_f32 v213, v216, v233
	v_cvt_pk_bf16_f32 v214, v234, v237
	v_cvt_pk_bf16_f32 v215, v238, v240
	v_cvt_pk_bf16_f32 v232, v112, v241
	v_cvt_pk_bf16_f32 v233, v242, v115
	v_cvt_pk_bf16_f32 v234, v116, v117
	v_cvt_pk_bf16_f32 v235, v118, v243
	v_cvt_pk_bf16_f32 v116, v119, v120
	v_cvt_pk_bf16_f32 v117, v121, v122
	v_cvt_pk_bf16_f32 v118, v123, v124
	v_cvt_pk_bf16_f32 v119, v125, v126
	v_add_u32_e32 v112, s39, v205
	ds_read_b64_tr_b16 v[120:121], v112 offset:0
	ds_read_b64_tr_b16 v[122:123], v112 offset:0x800
	ds_read_b64_tr_b16 v[124:125], v112 offset:0x1000
	ds_read_b64_tr_b16 v[126:127], v112 offset:0x1800
	ds_read_b64_tr_b16 v[236:237], v112 offset:0x2000
	ds_read_b64_tr_b16 v[238:239], v112 offset:0x2800
	ds_read_b64_tr_b16 v[240:241], v112 offset:0x3000
	ds_read_b64_tr_b16 v[242:243], v112 offset:0x3800
	s_cmp_gt_u32 s44, 60
	s_cselect_b64 s[52:53], -1, 0
	s_and_b64 vcc, exec, s[52:53]
	s_cbranch_vccnz .LBB0_204
	s_add_i32 s10, s56, 0x8000
	s_and_b32 s10, s10, 0x1ffff
	s_add_i32 s12, s21, s10
	v_lshl_add_u64 v[174:175], v[174:175], 0, s[68:69]
	s_add_i32 m0, s12, 0x4000
	s_mov_b64 s[10:11], 0x4040000
	global_load_lds_dwordx4 v[174:175], off
	v_lshl_add_u64 v[174:175], v[172:173], 0, s[10:11]
	s_mov_b32 m0, s12
	s_mov_b64 s[10:11], 0x4040080
	global_load_lds_dwordx4 v[174:175], off
	v_lshl_add_u64 v[174:175], v[176:177], 0, s[68:69]
	s_add_i32 m0, s12, 0x4400
	v_lshl_add_u64 v[172:173], v[172:173], 0, s[10:11]
	global_load_lds_dwordx4 v[174:175], off
	s_add_i32 m0, s12, 0x400
	s_nop 0
	global_load_lds_dwordx4 v[172:173], off
; #define SBAR() __builtin_amdgcn_sched_barrier(0)
; template <int OFF> __device__ __forceinline__ s16x4 tr_read(int vb) { s16x4 r; asm volatile("ds_read_b64_tr_b16 %0, %1 offset:%2" : "=&v"(r) : "v"(vb), "i"(OFF) : "memory"); return r; }
; template <bool FIRST> __device__ __forceinline__ void partialSM(f32x16& p0, f32x16& p1, float& m_reg, f32x16& negm, float& alpha) {
;   float pmax = p0[0];
; #pragma unroll
;   for (int r = 1; r < 16; ++r) pmax = fmaxf(pmax, p0[r]);
; #pragma unroll
;   for (int r = 0; r < 16; ++r) pmax = fmaxf(pmax, p1[r]);
;   { auto rr = __builtin_amdgcn_permlane32_swap(__float_as_uint(pmax), __float_as_uint(pmax), false, false);
;     pmax = fmaxf(__uint_as_float(rr[0]), __uint_as_float(rr[1])); }
;   alpha = 1.f;
;   if (FIRST || __builtin_expect(__any(pmax > THR), 0)) { const float dl = FIRST ? pmax : fmaxf(pmax, 0.f); m_reg += dl; if (!FIRST) alpha = __builtin_amdgcn_exp2f(-dl);
; template <int D0> __device__ __forceinline__ void pv_one(f32x16& od, int vb, bf16x8 pa0, bf16x8 pa1, bf16x8 pa2, bf16x8 pa3) {
;   const s16x4 l0 = tr_read<v_rd_off(D0, 0, 0)>(vb), h0 = tr_read<v_rd_off(D0, 0, 1)>(vb), l1 = tr_read<v_rd_off(D0, 1, 0)>(vb), h1 = tr_read<v_rd_off(D0, 1, 1)>(vb);
;   const s16x4 l2 = tr_read<v_rd_off(D0, 2, 0)>(vb), h2 = tr_read<v_rd_off(D0, 2, 1)>(vb), l3 = tr_read<v_rd_off(D0, 3, 0)>(vb), h3 = tr_read<v_rd_off(D0, 3, 1)>(vb);
;   asm volatile("s_waitcnt lgkmcnt(0)" ::: "memory"); SBAR();
;   od = __builtin_amdgcn_mfma_f32_32x32x16_bf16(pa0, ATT_PK(l0, h0), od, 0, 0, 0);
;   od = __builtin_amdgcn_mfma_f32_32x32x16_bf16(pa1, ATT_PK(l1, h1), od, 0, 0, 0);
;   od = __builtin_amdgcn_mfma_f32_32x32x16_bf16(pa2, ATT_PK(l2, h2), od, 0, 0, 0);
;   od = __builtin_amdgcn_mfma_f32_32x32x16_bf16(pa3, ATT_PK(l3, h3), od, 0, 0, 0);
; }
; __device__ __forceinline__ void pv_d0(f32x16* o, int vb, bf16x8 pa0, bf16x8 pa1, bf16x8 pa2, bf16x8 pa3) {
;   pv_one<0>(o[0], vb, pa0, pa1, pa2, pa3); pv_one<1>(o[1], vb, pa0, pa1, pa2, pa3); pv_one<2>(o[2], vb, pa0, pa1, pa2, pa3); pv_one<3>(o[3], vb, pa0, pa1, pa2, pa3);
; }
.LBB0_204:
	s_waitcnt lgkmcnt(0)
	s_nop 0
	v_mfma_f32_32x32x16_bf16 v[0:15], v[250:253], v[120:123], v[0:15]
	ds_read_b64_tr_b16 v[120:121], v112 offset:0x200
	ds_read_b64_tr_b16 v[122:123], v112 offset:0xa00
	v_mfma_f32_32x32x16_bf16 v[0:15], v[212:215], v[124:127], v[0:15]
	ds_read_b64_tr_b16 v[124:125], v112 offset:0x1200
	ds_read_b64_tr_b16 v[126:127], v112 offset:0x1a00
	v_mfma_f32_32x32x16_bf16 v[0:15], v[232:235], v[236:239], v[0:15]
	ds_read_b64_tr_b16 v[236:237], v112 offset:0x2200
	ds_read_b64_tr_b16 v[238:239], v112 offset:0x2a00
	v_mfma_f32_32x32x16_bf16 v[0:15], v[116:119], v[240:243], v[0:15]
	ds_read_b64_tr_b16 v[240:241], v112 offset:0x3200
	ds_read_b64_tr_b16 v[242:243], v112 offset:0x3a00
	s_waitcnt lgkmcnt(0)
	v_mfma_f32_32x32x16_bf16 v[48:63], v[250:253], v[120:123], v[48:63]
	ds_read_b64_tr_b16 v[120:121], v112 offset:0x400
	ds_read_b64_tr_b16 v[122:123], v112 offset:0xc00
	v_mfma_f32_32x32x16_bf16 v[48:63], v[212:215], v[124:127], v[48:63]
	ds_read_b64_tr_b16 v[124:125], v112 offset:0x1400
	ds_read_b64_tr_b16 v[126:127], v112 offset:0x1c00
	v_mfma_f32_32x32x16_bf16 v[48:63], v[232:235], v[236:239], v[48:63]
	ds_read_b64_tr_b16 v[236:237], v112 offset:0x2400
	ds_read_b64_tr_b16 v[238:239], v112 offset:0x2c00
	v_mfma_f32_32x32x16_bf16 v[48:63], v[116:119], v[240:243], v[48:63]
	ds_read_b64_tr_b16 v[240:241], v112 offset:0x3400
	ds_read_b64_tr_b16 v[242:243], v112 offset:0x3c00
	s_waitcnt lgkmcnt(0)
	v_mfma_f32_32x32x16_bf16 v[32:47], v[250:253], v[120:123], v[32:47]
	ds_read_b64_tr_b16 v[120:121], v112 offset:0x600
	ds_read_b64_tr_b16 v[122:123], v112 offset:0xe00
	v_mfma_f32_32x32x16_bf16 v[32:47], v[212:215], v[124:127], v[32:47]
	ds_read_b64_tr_b16 v[124:125], v112 offset:0x1600
	ds_read_b64_tr_b16 v[126:127], v112 offset:0x1e00
	v_mfma_f32_32x32x16_bf16 v[32:47], v[232:235], v[236:239], v[32:47]
	ds_read_b64_tr_b16 v[236:237], v112 offset:0x2600
	ds_read_b64_tr_b16 v[238:239], v112 offset:0x2e00
	v_mfma_f32_32x32x16_bf16 v[32:47], v[116:119], v[240:243], v[32:47]
	ds_read_b64_tr_b16 v[240:241], v112 offset:0x3600
	ds_read_b64_tr_b16 v[242:243], v112 offset:0x3e00
	s_waitcnt lgkmcnt(0)
	v_mfma_f32_32x32x16_bf16 v[16:31], v[250:253], v[120:123], v[16:31]
	v_max_f32_e32 v112, v129, v129
	v_max_f32_e32 v115, v128, v128
	v_max_f32_e32 v112, v115, v112
	v_max3_f32 v112, v112, v130, v131
	v_max3_f32 v112, v112, v132, v133
	v_max3_f32 v112, v112, v134, v135
	v_max3_f32 v112, v112, v136, v137
	v_mfma_f32_32x32x16_bf16 v[16:31], v[212:215], v[124:127], v[16:31]
	v_max3_f32 v112, v112, v138, v139
	v_max3_f32 v112, v112, v140, v141
	v_max3_f32 v112, v112, v142, v143
	v_max3_f32 v112, v112, v96, v97
	v_max3_f32 v112, v112, v98, v99
	v_max3_f32 v112, v112, v100, v101
	v_max3_f32 v112, v112, v102, v103
	v_mfma_f32_32x32x16_bf16 v[16:31], v[232:235], v[236:239], v[16:31]
	v_max3_f32 v112, v112, v104, v105
	v_max3_f32 v112, v112, v106, v107
	v_max3_f32 v112, v112, v108, v109
	v_max3_f32 v112, v112, v110, v111
	v_mov_b32_e32 v115, v112
	s_nop 1
	v_permlane32_swap_b32_e32 v112, v115
	v_mfma_f32_32x32x16_bf16 v[16:31], v[116:119], v[240:243], v[16:31]
	v_max_f32_e32 v115, v115, v115
	v_max_f32_e32 v112, v112, v112
	v_max_f32_e32 v115, v112, v115
	v_cmp_lt_f32_e32 vcc, s19, v115
	v_mov_b32_e32 v112, 1.0
	s_cbranch_vccnz .LBB0_216
	v_cmp_gt_f32_e32 vcc, 1.0, v112
	s_cbranch_vccz .LBB0_209
